# v86 + earlywb0: first workgroup of each XCD to arrive at a grid barrier starts one extra L2 write-back ahead of the leader's
# baseline (speedup 1.0000x reference)
.LBB0_748:
	s_or_b64 exec, exec, s[14:15]
	v_cvt_f32_u32_e32 v6, v4
	s_waitcnt vmcnt(0)
	v_readfirstlane_b32 s7, v5
	v_sub_u32_e32 v5, 0, v4
	v_rcp_iflag_f32_e32 v6, v6
	v_add_u32_e32 v7, s7, v3
	v_mul_f32_e32 v6, 0x4f7ffffe, v6
	v_cvt_u32_f32_e32 v6, v6
	v_mul_lo_u32 v3, v5, v6
	v_mul_hi_u32 v3, v6, v3
	v_add_u32_e32 v3, v6, v3
	v_mul_hi_u32 v3, v7, v3
	v_mul_lo_u32 v5, v3, v4
	v_sub_u32_e32 v5, v7, v5
	v_add_u32_e32 v6, 1, v3
	v_cmp_ge_u32_e32 vcc, v5, v4
	s_nop 1
	v_cndmask_b32_e32 v3, v3, v6, vcc
	v_sub_u32_e32 v6, v5, v4
	v_cndmask_b32_e32 v5, v5, v6, vcc
	v_add_u32_e32 v6, 1, v3
	v_cmp_ge_u32_e32 vcc, v5, v4
	v_add_u32_e32 v5, 1, v7
	s_nop 0
	v_cndmask_b32_e32 v3, v3, v6, vcc
	v_mul_lo_u32 v6, v4, v3
	v_add_u32_e32 v4, v6, v4
	v_cmp_ne_u32_e32 vcc, v5, v4
	s_and_saveexec_b64 s[8:9], vcc
	s_xor_b64 s[14:15], exec, s[8:9]
	s_cbranch_execz .LBB0_762
	v_sub_u32_e32 v2, v7, v6
	v_cmp_eq_u32_e32 vcc, 0, v2
	s_cbranch_vccz .Lmy_ewb_0
	buffer_wbl2 sc1
.Lmy_ewb_0:
	v_readlane_b32 s8, v255, 6
	v_readlane_b32 s9, v255, 7
	s_waitcnt lgkmcnt(0)
	s_nop 3
	global_load_dword v2, v181, s[8:9] sc1
	s_waitcnt vmcnt(0)
	v_cmp_eq_u32_e32 vcc, v2, v3
	s_and_saveexec_b64 s[18:19], vcc
	s_cbranch_execz .LBB0_761
	s_mov_b32 s7, 1
	s_mov_b64 s[22:23], 0
	s_branch .LBB0_752

.LBB0_963:
	s_or_b64 exec, exec, s[14:15]
	v_cvt_f32_u32_e32 v6, v4
	s_waitcnt vmcnt(0)
	v_readfirstlane_b32 s6, v5
	v_sub_u32_e32 v5, 0, v4
	v_rcp_iflag_f32_e32 v6, v6
	v_add_u32_e32 v7, s6, v3
	v_mul_f32_e32 v6, 0x4f7ffffe, v6
	v_cvt_u32_f32_e32 v6, v6
	v_mul_lo_u32 v3, v5, v6
	v_mul_hi_u32 v3, v6, v3
	v_add_u32_e32 v3, v6, v3
	v_mul_hi_u32 v3, v7, v3
	v_mul_lo_u32 v5, v3, v4
	v_sub_u32_e32 v5, v7, v5
	v_add_u32_e32 v6, 1, v3
	v_cmp_ge_u32_e32 vcc, v5, v4
	s_nop 1
	v_cndmask_b32_e32 v3, v3, v6, vcc
	v_sub_u32_e32 v6, v5, v4
	v_cndmask_b32_e32 v5, v5, v6, vcc
	v_add_u32_e32 v6, 1, v3
	v_cmp_ge_u32_e32 vcc, v5, v4
	v_add_u32_e32 v5, 1, v7
	s_nop 0
	v_cndmask_b32_e32 v3, v3, v6, vcc
	v_mul_lo_u32 v6, v4, v3
	v_add_u32_e32 v4, v6, v4
	v_cmp_ne_u32_e32 vcc, v5, v4
	s_and_saveexec_b64 s[6:7], vcc
	s_xor_b64 s[14:15], exec, s[6:7]
	s_cbranch_execz .LBB0_977
	v_sub_u32_e32 v2, v7, v6
	v_cmp_eq_u32_e32 vcc, 0, v2
	s_cbranch_vccz .Lmy_ewb_2
	buffer_wbl2 sc1
.Lmy_ewb_2:
	v_readlane_b32 s6, v255, 6
	v_readlane_b32 s7, v255, 7
	s_waitcnt lgkmcnt(0)
	s_nop 3
	global_load_dword v2, v181, s[6:7] sc1
	s_waitcnt vmcnt(0)
	v_cmp_eq_u32_e32 vcc, v2, v3
	s_and_saveexec_b64 s[18:19], vcc
	s_cbranch_execz .LBB0_976
	s_mov_b32 s6, 1
	s_mov_b64 s[22:23], 0
	s_branch .LBB0_967

.LBB0_1372:
	s_or_b64 exec, exec, s[18:19]
	v_cvt_f32_u32_e32 v6, v4
	s_waitcnt vmcnt(0)
	v_readfirstlane_b32 s7, v5
	v_sub_u32_e32 v5, 0, v4
	v_rcp_iflag_f32_e32 v6, v6
	v_add_u32_e32 v7, s7, v3
	v_mul_f32_e32 v6, 0x4f7ffffe, v6
	v_cvt_u32_f32_e32 v6, v6
	v_mul_lo_u32 v3, v5, v6
	v_mul_hi_u32 v3, v6, v3
	v_add_u32_e32 v3, v6, v3
	v_mul_hi_u32 v3, v7, v3
	v_mul_lo_u32 v5, v3, v4
	v_sub_u32_e32 v5, v7, v5
	v_add_u32_e32 v6, 1, v3
	v_cmp_ge_u32_e32 vcc, v5, v4
	s_nop 1
	v_cndmask_b32_e32 v3, v3, v6, vcc
	v_sub_u32_e32 v6, v5, v4
	v_cndmask_b32_e32 v5, v5, v6, vcc
	v_add_u32_e32 v6, 1, v3
	v_cmp_ge_u32_e32 vcc, v5, v4
	v_add_u32_e32 v5, 1, v7
	s_nop 0
	v_cndmask_b32_e32 v3, v3, v6, vcc
	v_mul_lo_u32 v6, v4, v3
	v_add_u32_e32 v4, v6, v4
	v_cmp_ne_u32_e32 vcc, v5, v4
	s_and_saveexec_b64 s[8:9], vcc
	s_xor_b64 s[18:19], exec, s[8:9]
	s_cbranch_execz .LBB0_1386
	v_sub_u32_e32 v2, v7, v6
	v_cmp_eq_u32_e32 vcc, 0, v2
	s_cbranch_vccz .Lmy_ewb_3
	buffer_wbl2 sc1
.Lmy_ewb_3:
	v_readlane_b32 s8, v255, 6
	v_readlane_b32 s9, v255, 7
	s_waitcnt lgkmcnt(0)
	s_nop 3
	global_load_dword v2, v181, s[8:9] sc1
	s_waitcnt vmcnt(0)
	v_cmp_eq_u32_e32 vcc, v2, v3
	s_and_saveexec_b64 s[22:23], vcc
	s_cbranch_execz .LBB0_1385
	s_mov_b32 s7, 1
	s_mov_b64 s[24:25], 0
	s_branch .LBB0_1376

.LBB0_1517:
	s_or_b64 exec, exec, s[10:11]
	v_cvt_f32_u32_e32 v6, v4
	s_waitcnt vmcnt(0)
	v_readfirstlane_b32 s6, v5
	v_sub_u32_e32 v5, 0, v4
	v_rcp_iflag_f32_e32 v6, v6
	v_add_u32_e32 v7, s6, v3
	v_mul_f32_e32 v6, 0x4f7ffffe, v6
	v_cvt_u32_f32_e32 v6, v6
	v_mul_lo_u32 v3, v5, v6
	v_mul_hi_u32 v3, v6, v3
	v_add_u32_e32 v3, v6, v3
	v_mul_hi_u32 v3, v7, v3
	v_mul_lo_u32 v5, v3, v4
	v_sub_u32_e32 v5, v7, v5
	v_add_u32_e32 v6, 1, v3
	v_cmp_ge_u32_e32 vcc, v5, v4
	s_nop 1
	v_cndmask_b32_e32 v3, v3, v6, vcc
	v_sub_u32_e32 v6, v5, v4
	v_cndmask_b32_e32 v5, v5, v6, vcc
	v_add_u32_e32 v6, 1, v3
	v_cmp_ge_u32_e32 vcc, v5, v4
	v_add_u32_e32 v5, 1, v7
	s_nop 0
	v_cndmask_b32_e32 v3, v3, v6, vcc
	v_mul_lo_u32 v6, v4, v3
	v_add_u32_e32 v4, v6, v4
	v_cmp_ne_u32_e32 vcc, v5, v4
	s_and_saveexec_b64 s[6:7], vcc
	s_xor_b64 s[10:11], exec, s[6:7]
	s_cbranch_execz .LBB0_1531
	v_sub_u32_e32 v2, v7, v6
	v_cmp_eq_u32_e32 vcc, 0, v2
	s_cbranch_vccz .Lmy_ewb_4
	buffer_wbl2 sc1
.Lmy_ewb_4:
	v_readlane_b32 s6, v255, 6
	v_readlane_b32 s7, v255, 7
	s_waitcnt lgkmcnt(0)
	s_nop 3
	global_load_dword v2, v181, s[6:7] sc1
	s_waitcnt vmcnt(0)
	v_cmp_eq_u32_e32 vcc, v2, v3
	s_and_saveexec_b64 s[14:15], vcc
	s_cbranch_execz .LBB0_1530
	s_mov_b32 s6, 1
	s_mov_b64 s[18:19], 0
	s_branch .LBB0_1521
